# merge phase: the eight bridge-gate loads of each j-epilogue issued together instead of eight serialized load/wait steps
# speedup vs baseline: 1.0039x; 1.0039x over previous
.LBB0_1170:
	v_lshl_add_u64 v[120:121], s[92:93], 0, v[102:103]
	v_add_co_u32_e32 v120, vcc, 0xcf01000, v120
	s_waitcnt lgkmcnt(0)
	s_nop 0
	v_addc_co_u32_e32 v121, vcc, 0, v121, vcc
	s_barrier
	v_lshl_add_u64 v[128:129], s[92:93], 0, v[100:101]
	v_add_co_u32_e32 v128, vcc, 0xcf01000, v128
	s_nop 1
	v_addc_co_u32_e32 v129, vcc, 0, v129, vcc
	global_load_dwordx2 v[136:137], v[120:121], off offset:3584
	global_load_dwordx2 v[138:139], v[120:121], off offset:3600
	global_load_dwordx2 v[140:141], v[120:121], off offset:3616
	global_load_dwordx2 v[142:143], v[120:121], off offset:3632
	global_load_dwordx2 v[144:145], v[128:129], off offset:3584
	global_load_dwordx2 v[146:147], v[128:129], off offset:3600
	global_load_dwordx2 v[148:149], v[128:129], off offset:3616
	global_load_dwordx2 v[150:151], v[128:129], off offset:3632
	s_mov_b32 s4, 0xcf01000
	s_add_u32 s42, s42, 0x100000
	s_addc_u32 s43, s43, 0
	s_add_u32 s40, s40, 0x1200000
	v_lshl_add_u64 v[102:103], v[102:103], 0, s[36:37]
	s_addc_u32 s41, s41, 0
	s_mov_b64 s[38:39], 0
	s_waitcnt vmcnt(7)
	v_mov_b64_e32 v[122:123], v[136:137]
	v_lshlrev_b32_e32 v96, 16, v122
	v_mul_f32_e32 v96, 0xbfb8aa3b, v96
	v_exp_f32_e32 v96, v96
	s_nop 0
	v_add_f32_e32 v96, 1.0, v96
	v_rcp_f32_e32 v124, v96
	v_and_b32_e32 v96, 0xffff0000, v122
	v_mul_f32_e32 v96, 0xbfb8aa3b, v96
	v_exp_f32_e32 v96, v96
	s_nop 0
	v_add_f32_e32 v96, 1.0, v96
	v_rcp_f32_e32 v125, v96
	s_nop 0
	v_pk_fma_f32 v[116:117], v[16:17], v[124:125], v[116:117]
	v_lshlrev_b32_e32 v16, 16, v123
	v_and_b32_e32 v17, 0xffff0000, v123
	v_mul_f32_e32 v16, 0xbfb8aa3b, v16
	v_mul_f32_e32 v17, 0xbfb8aa3b, v17
	v_exp_f32_e32 v16, v16
	v_exp_f32_e32 v17, v17
	v_add_f32_e32 v16, 1.0, v16
	v_add_f32_e32 v17, 1.0, v17
	v_rcp_f32_e32 v16, v16
	v_rcp_f32_e32 v17, v17
	s_nop 0
	v_pk_fma_f32 v[118:119], v[18:19], v[16:17], v[118:119]
	s_waitcnt vmcnt(6)
	v_mov_b64_e32 v[16:17], v[138:139]
	s_nop 0
	v_lshlrev_b32_e32 v18, 16, v16
	v_and_b32_e32 v16, 0xffff0000, v16
	v_mul_f32_e32 v16, 0xbfb8aa3b, v16
	v_exp_f32_e32 v16, v16
	v_mul_f32_e32 v18, 0xbfb8aa3b, v18
	v_exp_f32_e32 v18, v18
	v_add_f32_e32 v16, 1.0, v16
	v_rcp_f32_e32 v19, v16
	v_lshlrev_b32_e32 v16, 16, v17
	v_and_b32_e32 v17, 0xffff0000, v17
	v_mul_f32_e32 v16, 0xbfb8aa3b, v16
	v_mul_f32_e32 v17, 0xbfb8aa3b, v17
	v_exp_f32_e32 v16, v16
	v_exp_f32_e32 v17, v17
	v_add_f32_e32 v18, 1.0, v18
	v_rcp_f32_e32 v18, v18
	v_add_f32_e32 v16, 1.0, v16
	v_add_f32_e32 v17, 1.0, v17
	v_rcp_f32_e32 v16, v16
	v_rcp_f32_e32 v17, v17
	v_pk_fma_f32 v[112:113], v[20:21], v[18:19], v[112:113]
	v_pk_fma_f32 v[114:115], v[22:23], v[16:17], v[114:115]
	s_waitcnt vmcnt(5)
	v_mov_b64_e32 v[16:17], v[140:141]
	s_nop 0
	v_lshlrev_b32_e32 v18, 16, v16
	v_and_b32_e32 v16, 0xffff0000, v16
	v_mul_f32_e32 v16, 0xbfb8aa3b, v16
	v_exp_f32_e32 v16, v16
	v_mul_f32_e32 v18, 0xbfb8aa3b, v18
	v_exp_f32_e32 v18, v18
	v_add_f32_e32 v16, 1.0, v16
	v_rcp_f32_e32 v19, v16
	v_lshlrev_b32_e32 v16, 16, v17
	v_and_b32_e32 v17, 0xffff0000, v17
	v_mul_f32_e32 v16, 0xbfb8aa3b, v16
	v_mul_f32_e32 v17, 0xbfb8aa3b, v17
	v_exp_f32_e32 v16, v16
	v_exp_f32_e32 v17, v17
	v_add_f32_e32 v18, 1.0, v18
	v_rcp_f32_e32 v18, v18
	v_add_f32_e32 v16, 1.0, v16
	v_add_f32_e32 v17, 1.0, v17
	v_rcp_f32_e32 v16, v16
	v_rcp_f32_e32 v17, v17
	v_pk_fma_f32 v[108:109], v[24:25], v[18:19], v[108:109]
	v_pk_fma_f32 v[110:111], v[26:27], v[16:17], v[110:111]
	s_waitcnt vmcnt(4)
	v_mov_b64_e32 v[16:17], v[142:143]
	s_nop 0
	v_lshlrev_b32_e32 v18, 16, v16
	v_and_b32_e32 v16, 0xffff0000, v16
	v_mul_f32_e32 v16, 0xbfb8aa3b, v16
	v_exp_f32_e32 v16, v16
	v_mul_f32_e32 v18, 0xbfb8aa3b, v18
	v_exp_f32_e32 v18, v18
	v_add_f32_e32 v16, 1.0, v16
	v_rcp_f32_e32 v19, v16
	v_lshlrev_b32_e32 v16, 16, v17
	v_and_b32_e32 v17, 0xffff0000, v17
	v_mul_f32_e32 v16, 0xbfb8aa3b, v16
	v_mul_f32_e32 v17, 0xbfb8aa3b, v17
	v_exp_f32_e32 v16, v16
	v_exp_f32_e32 v17, v17
	v_add_f32_e32 v18, 1.0, v18
	v_rcp_f32_e32 v18, v18
	v_add_f32_e32 v16, 1.0, v16
	v_add_f32_e32 v17, 1.0, v17
	v_rcp_f32_e32 v16, v16
	v_rcp_f32_e32 v17, v17
	v_pk_fma_f32 v[106:107], v[28:29], v[18:19], v[106:107]
	v_pk_fma_f32 v[104:105], v[30:31], v[16:17], v[104:105]
	v_lshl_add_u64 v[16:17], s[92:93], 0, v[100:101]
	v_add_co_u32_e32 v16, vcc, s4, v16
	v_lshl_add_u64 v[100:101], v[100:101], 0, s[36:37]
	s_nop 0
	v_addc_co_u32_e32 v17, vcc, 0, v17, vcc
	s_waitcnt vmcnt(3)
	v_mov_b64_e32 v[18:19], v[144:145]
	s_nop 0
	v_lshlrev_b32_e32 v20, 16, v18
	v_and_b32_e32 v18, 0xffff0000, v18
	v_mul_f32_e32 v20, 0xbfb8aa3b, v20
	v_mul_f32_e32 v18, 0xbfb8aa3b, v18
	v_exp_f32_e32 v20, v20
	v_exp_f32_e32 v18, v18
	v_add_f32_e32 v20, 1.0, v20
	v_add_f32_e32 v18, 1.0, v18
	v_rcp_f32_e32 v20, v20
	v_rcp_f32_e32 v21, v18
	s_nop 0
	v_pk_fma_f32 v[92:93], v[0:1], v[20:21], v[92:93]
	v_lshlrev_b32_e32 v0, 16, v19
	v_and_b32_e32 v1, 0xffff0000, v19
	v_mul_f32_e32 v0, 0xbfb8aa3b, v0
	v_mul_f32_e32 v1, 0xbfb8aa3b, v1
	v_exp_f32_e32 v0, v0
	v_exp_f32_e32 v1, v1
	v_add_f32_e32 v0, 1.0, v0
	v_add_f32_e32 v1, 1.0, v1
	v_rcp_f32_e32 v0, v0
	v_rcp_f32_e32 v1, v1
	s_nop 0
	v_pk_fma_f32 v[94:95], v[2:3], v[0:1], v[94:95]
	s_waitcnt vmcnt(2)
	v_mov_b64_e32 v[0:1], v[146:147]
	s_nop 0
	v_lshlrev_b32_e32 v2, 16, v0
	v_and_b32_e32 v0, 0xffff0000, v0
	v_mul_f32_e32 v0, 0xbfb8aa3b, v0
	v_exp_f32_e32 v0, v0
	v_mul_f32_e32 v2, 0xbfb8aa3b, v2
	v_exp_f32_e32 v2, v2
	v_add_f32_e32 v0, 1.0, v0
	v_rcp_f32_e32 v3, v0
	v_lshlrev_b32_e32 v0, 16, v1
	v_and_b32_e32 v1, 0xffff0000, v1
	v_mul_f32_e32 v0, 0xbfb8aa3b, v0
	v_mul_f32_e32 v1, 0xbfb8aa3b, v1
	v_exp_f32_e32 v0, v0
	v_exp_f32_e32 v1, v1
	v_add_f32_e32 v2, 1.0, v2
	v_rcp_f32_e32 v2, v2
	v_add_f32_e32 v0, 1.0, v0
	v_add_f32_e32 v1, 1.0, v1
	v_rcp_f32_e32 v0, v0
	v_rcp_f32_e32 v1, v1
	v_pk_fma_f32 v[88:89], v[4:5], v[2:3], v[88:89]
	v_pk_fma_f32 v[90:91], v[6:7], v[0:1], v[90:91]
	s_waitcnt vmcnt(1)
	v_mov_b64_e32 v[0:1], v[148:149]
	s_nop 0
	v_lshlrev_b32_e32 v2, 16, v0
	v_and_b32_e32 v0, 0xffff0000, v0
	v_mul_f32_e32 v0, 0xbfb8aa3b, v0
	v_exp_f32_e32 v0, v0
	v_mul_f32_e32 v2, 0xbfb8aa3b, v2
	v_exp_f32_e32 v2, v2
	v_add_f32_e32 v0, 1.0, v0
	v_rcp_f32_e32 v3, v0
	v_lshlrev_b32_e32 v0, 16, v1
	v_and_b32_e32 v1, 0xffff0000, v1
	v_mul_f32_e32 v0, 0xbfb8aa3b, v0
	v_mul_f32_e32 v1, 0xbfb8aa3b, v1
	v_exp_f32_e32 v0, v0
	v_exp_f32_e32 v1, v1
	v_add_f32_e32 v2, 1.0, v2
	v_rcp_f32_e32 v2, v2
	v_add_f32_e32 v0, 1.0, v0
	v_add_f32_e32 v1, 1.0, v1
	v_rcp_f32_e32 v0, v0
	v_rcp_f32_e32 v1, v1
	v_pk_fma_f32 v[84:85], v[8:9], v[2:3], v[84:85]
	v_pk_fma_f32 v[86:87], v[10:11], v[0:1], v[86:87]
	s_waitcnt vmcnt(0)
	v_mov_b64_e32 v[0:1], v[150:151]
	s_nop 0
	v_lshlrev_b32_e32 v2, 16, v0
	v_and_b32_e32 v0, 0xffff0000, v0
	v_mul_f32_e32 v0, 0xbfb8aa3b, v0
	v_exp_f32_e32 v0, v0
	v_mul_f32_e32 v2, 0xbfb8aa3b, v2
	v_exp_f32_e32 v2, v2
	v_add_f32_e32 v0, 1.0, v0
	v_rcp_f32_e32 v3, v0
	v_lshlrev_b32_e32 v0, 16, v1
	v_and_b32_e32 v1, 0xffff0000, v1
	v_mul_f32_e32 v0, 0xbfb8aa3b, v0
	v_mul_f32_e32 v1, 0xbfb8aa3b, v1
	v_exp_f32_e32 v0, v0
	v_exp_f32_e32 v1, v1
	v_add_f32_e32 v2, 1.0, v2
	v_rcp_f32_e32 v2, v2
	v_add_f32_e32 v0, 1.0, v0
	v_add_f32_e32 v1, 1.0, v1
	v_rcp_f32_e32 v0, v0
	v_rcp_f32_e32 v1, v1
	v_pk_fma_f32 v[82:83], v[12:13], v[2:3], v[82:83]
	v_pk_fma_f32 v[80:81], v[14:15], v[0:1], v[80:81]
	v_add_co_u32_e64 v0, s[44:45], s7, 1
	s_nop 0
	v_readfirstlane_b32 s7, v0
	s_and_b64 vcc, exec, s[44:45]
	s_cbranch_vccnz .LBB0_1166
